# P1 proj GEMM: MFMA runs of the all-padding column half skipped in the last column tile
# baseline (speedup 1.0000x reference)
; #define PG8_STAGE(bufoff, gbase, voff) do { _Pragma("unroll") for (int _i = 0; _i < 2; ++_i) \
;         __builtin_amdgcn_global_load_lds((const unsigned*)((const char*)(gbase) + (voff)[_i]), (LAS unsigned*)(lds + (bufoff) + ldsw + _i * 8192), 16, 0, 0); } while (0)
; #define PG8_LDA(dst, b, h) do { _Pragma("unroll") for (int m = 0; m < 4; ++m) _Pragma("unroll") for (int k = 0; k < 2; ++k) dst[m][k] = *(const LAS bf16x8*)(lds + PG8_SA(b, h) + aoff + m * 2048 + k * 1024); } while (0)
; #define PG8_LDB(dst, b, h) do { _Pragma("unroll") for (int n = 0; n < 2; ++n) _Pragma("unroll") for (int k = 0; k < 2; ++k) dst[n][k] = *(const LAS bf16x8*)(lds + PG8_SB(b, h) + boff + n * 2048 + k * 1024); } while (0)
; #define PG8_MMA(ai, bj, At, Bt) do { __builtin_amdgcn_s_setprio(1); _Pragma("unroll") for (int m = 0; m < 4; ++m) _Pragma("unroll") for (int n = 0; n < 2; ++n) _Pragma("unroll") for (int k = 0; k < 2; ++k) \
;         acc[ai][bj][m][n] = __builtin_amdgcn_mfma_f32_16x16x32_bf16(Bt[n][k], At[m][k], acc[ai][bj][m][n], 0, 0, 0); __builtin_amdgcn_s_setprio(0); } while (0)
; #define PG8_WAIT_V(n) asm volatile("s_waitcnt vmcnt(" #n ")" ::: "memory")
; #define PG8_WAIT_L(n) asm volatile("s_waitcnt lgkmcnt(" #n ")" ::: "memory")
; #define PG8_BAR __builtin_amdgcn_s_barrier()
; #define PG8_SCHED __builtin_amdgcn_sched_barrier(0)
; DI void gemm_phase(LAS unsigned char* lds, const Gemm g, const StaticOrder& S, const Epi& E) {
;     ...
;             PG8_LDB(B0, 0, 0); PG8_LDB(B1, 0, 1); PG8_SCHED; PG8_LDA(At, 0, 0); PG8_STAGE(PG8_SA(1, 1), a1 + hsA, voffA);
;             PG8_WAIT_V(8); PG8_WAIT_L(0); PG8_BAR; PG8_MMA(0, 0, At, B0); PG8_MMA(0, 1, At, B1); PG8_BAR; PG8_SCHED;
;     ...
;         for (int a = 0; a < 2; ++a)
; #pragma unroll
;             for (int b = 0; b < 2; ++b)
; #pragma unroll
;                 for (int m = 0; m < 4; ++m)
; #pragma unroll
;                     for (int n = 0; n < 2; ++n) acc[a][b][m][n] = (f32x4){0.f, 0.f, 0.f, 0.f};
.LBB0_176:
	s_ashr_i32 s23, s22, 31
	s_lshl_b64 s[24:25], s[22:23], 20
	s_add_u32 s24, s62, s24
	s_addc_u32 s25, s63, s25
	s_and_b64 s[26:27], s[2:3], exec
	s_cselect_b32 s5, s25, s31
	s_cselect_b32 s23, s24, s30
	s_ashr_i32 s21, s20, 31
	s_lshl_b64 s[26:27], s[20:21], 20
	s_add_u32 s26, s0, s26
	s_addc_u32 s27, s1, s27
	s_and_b64 s[38:39], s[2:3], exec
	s_cselect_b32 s21, s27, s35
	s_cselect_b32 s29, s26, s34
	s_add_u32 s30, s30, 0x80080
	s_addc_u32 s31, s31, 0
	s_add_u32 s54, s34, 0x100
	v_mov_b32_e32 v0, 0
	s_addc_u32 s55, s35, 0
	s_mov_b32 s56, -2
	v_mov_b32_e32 v1, v0
	v_mov_b32_e32 v2, v0
	v_mov_b32_e32 v3, v0
	v_mov_b32_e32 v4, v0
	v_mov_b32_e32 v5, v0
	v_mov_b32_e32 v6, v0
	v_mov_b32_e32 v7, v0
	v_mov_b32_e32 v8, v0
	v_mov_b32_e32 v9, v0
	v_mov_b32_e32 v10, v0
	v_mov_b32_e32 v11, v0
	v_mov_b32_e32 v16, v0
	v_mov_b32_e32 v17, v0
	v_mov_b32_e32 v18, v0
	v_mov_b32_e32 v19, v0
	v_mov_b32_e32 v24, v0
	v_mov_b32_e32 v25, v0
	v_mov_b32_e32 v26, v0
	v_mov_b32_e32 v27, v0
	v_mov_b32_e32 v32, v0
	v_mov_b32_e32 v33, v0
	v_mov_b32_e32 v34, v0
	v_mov_b32_e32 v35, v0
	v_mov_b32_e32 v40, v0
	v_mov_b32_e32 v41, v0
	v_mov_b32_e32 v42, v0
	v_mov_b32_e32 v43, v0
	v_mov_b32_e32 v48, v0
	v_mov_b32_e32 v49, v0
	v_mov_b32_e32 v50, v0
	v_mov_b32_e32 v51, v0
	v_mov_b32_e32 v12, v0
	v_mov_b32_e32 v13, v0
	v_mov_b32_e32 v14, v0
	v_mov_b32_e32 v15, v0
	v_mov_b32_e32 v20, v0
	v_mov_b32_e32 v21, v0
	v_mov_b32_e32 v22, v0
	v_mov_b32_e32 v23, v0
	v_mov_b32_e32 v28, v0
	v_mov_b32_e32 v29, v0
	v_mov_b32_e32 v30, v0
	v_mov_b32_e32 v31, v0
	v_mov_b32_e32 v36, v0
	v_mov_b32_e32 v37, v0
	v_mov_b32_e32 v38, v0
	v_mov_b32_e32 v39, v0
	v_mov_b32_e32 v44, v0
	v_mov_b32_e32 v45, v0
	v_mov_b32_e32 v46, v0
	v_mov_b32_e32 v47, v0
	v_mov_b32_e32 v52, v0
	v_mov_b32_e32 v53, v0
	v_mov_b32_e32 v54, v0
	v_mov_b32_e32 v55, v0
	v_mov_b32_e32 v56, v0
	v_mov_b32_e32 v57, v0
	v_mov_b32_e32 v58, v0
	v_mov_b32_e32 v59, v0
	v_mov_b32_e32 v60, v0
	v_mov_b32_e32 v61, v0
	v_mov_b32_e32 v62, v0
	v_mov_b32_e32 v63, v0
	v_mov_b32_e32 v64, v0
	v_mov_b32_e32 v65, v0
	v_mov_b32_e32 v66, v0
	v_mov_b32_e32 v67, v0
	v_mov_b32_e32 v68, v0
	v_mov_b32_e32 v69, v0
	v_mov_b32_e32 v70, v0
	v_mov_b32_e32 v71, v0
	v_mov_b32_e32 v72, v0
	v_mov_b32_e32 v73, v0
	v_mov_b32_e32 v74, v0
	v_mov_b32_e32 v75, v0
	v_mov_b32_e32 v80, v0
	v_mov_b32_e32 v81, v0
	v_mov_b32_e32 v82, v0
	v_mov_b32_e32 v83, v0
	v_mov_b32_e32 v88, v0
	v_mov_b32_e32 v89, v0
	v_mov_b32_e32 v90, v0
	v_mov_b32_e32 v91, v0
	v_mov_b32_e32 v96, v0
	v_mov_b32_e32 v97, v0
	v_mov_b32_e32 v98, v0
	v_mov_b32_e32 v99, v0
	v_mov_b32_e32 v104, v0
	v_mov_b32_e32 v105, v0
	v_mov_b32_e32 v106, v0
	v_mov_b32_e32 v107, v0
	v_mov_b32_e32 v112, v0
	v_mov_b32_e32 v113, v0
	v_mov_b32_e32 v114, v0
	v_mov_b32_e32 v115, v0
	v_mov_b32_e32 v76, v0
	v_mov_b32_e32 v77, v0
	v_mov_b32_e32 v78, v0
	v_mov_b32_e32 v79, v0
	v_mov_b32_e32 v84, v0
	v_mov_b32_e32 v85, v0
	v_mov_b32_e32 v86, v0
	v_mov_b32_e32 v87, v0
	v_mov_b32_e32 v92, v0
	v_mov_b32_e32 v93, v0
	v_mov_b32_e32 v94, v0
	v_mov_b32_e32 v95, v0
	v_mov_b32_e32 v100, v0
	v_mov_b32_e32 v101, v0
	v_mov_b32_e32 v102, v0
	v_mov_b32_e32 v103, v0
	v_mov_b32_e32 v108, v0
	v_mov_b32_e32 v109, v0
	v_mov_b32_e32 v110, v0
	v_mov_b32_e32 v111, v0
	v_mov_b32_e32 v116, v0
	v_mov_b32_e32 v117, v0
	v_mov_b32_e32 v118, v0
	v_mov_b32_e32 v119, v0
	v_mov_b32_e32 v120, v0
	v_mov_b32_e32 v121, v0
	v_mov_b32_e32 v122, v0
	v_mov_b32_e32 v123, v0
	v_mov_b32_e32 v124, v0
	v_mov_b32_e32 v125, v0
	v_mov_b32_e32 v126, v0
	v_mov_b32_e32 v127, v0
	s_cmp_eq_u32 s4, 10
	s_cselect_b64 vcc, -1, 0
.LBB0_177:
	ds_read_b128 v[152:155], v149
	ds_read_b128 v[156:159], v149 offset:1024
	ds_read_b128 v[160:163], v149 offset:2048
	ds_read_b128 v[170:173], v149 offset:3072
	ds_read_b128 v[174:177], v150
	ds_read_b128 v[178:181], v150 offset:1024
	ds_read_b128 v[182:185], v150 offset:2048
	ds_read_b128 v[186:189], v150 offset:3072
	s_add_u32 s34, s30, 0xfff80080
	s_addc_u32 s35, s31, -1
	s_cmp_eq_u32 s56, 28
	s_cselect_b32 s39, s5, s35
	s_cselect_b32 s38, s23, s34
	s_cselect_b32 s35, s21, s55
	s_cselect_b32 s34, s29, s54
	s_add_i32 m0, s13, 0xc000
	ds_read_b128 v[190:193], v151
	ds_read_b128 v[194:197], v151 offset:1024
	ds_read_b128 v[198:201], v151 offset:2048
	ds_read_b128 v[202:205], v151 offset:3072
	ds_read_b128 v[206:209], v151 offset:4096
	ds_read_b128 v[210:213], v151 offset:5120
	ds_read_b128 v[214:217], v151 offset:6144
	ds_read_b128 v[218:221], v151 offset:7168
	global_load_lds_dwordx4 v136, s[30:31]
	s_add_i32 m0, s13, 0xe000
	s_nop 0
	global_load_lds_dwordx4 v138, s[30:31]
	s_waitcnt vmcnt(8)
	s_waitcnt lgkmcnt(0)
	s_barrier
	s_setprio 1
	s_waitcnt lgkmcnt(0)
	v_mfma_f32_16x16x32_bf16 v[124:127], v[152:155], v[190:193], v[124:127]
	v_mfma_f32_16x16x32_bf16 v[124:127], v[156:159], v[194:197], v[124:127]
	v_mfma_f32_16x16x32_bf16 v[120:123], v[170:173], v[194:197], v[120:123]
	v_mfma_f32_16x16x32_bf16 v[120:123], v[160:163], v[190:193], v[120:123]
	v_mfma_f32_16x16x32_bf16 v[108:111], v[160:163], v[198:201], v[108:111]
	v_mfma_f32_16x16x32_bf16 v[108:111], v[170:173], v[202:205], v[108:111]
	v_mfma_f32_16x16x32_bf16 v[116:119], v[156:159], v[202:205], v[116:119]
	v_mfma_f32_16x16x32_bf16 v[116:119], v[152:155], v[198:201], v[116:119]
	v_mfma_f32_16x16x32_bf16 v[100:103], v[152:155], v[206:209], v[100:103]
	v_mfma_f32_16x16x32_bf16 v[100:103], v[156:159], v[210:213], v[100:103]
	v_mfma_f32_16x16x32_bf16 v[92:95], v[170:173], v[210:213], v[92:95]
	v_mfma_f32_16x16x32_bf16 v[92:95], v[160:163], v[206:209], v[92:95]
	v_mfma_f32_16x16x32_bf16 v[76:79], v[160:163], v[214:217], v[76:79]
	v_mfma_f32_16x16x32_bf16 v[76:79], v[170:173], v[218:221], v[76:79]
	v_mfma_f32_16x16x32_bf16 v[84:87], v[156:159], v[218:221], v[84:87]
	v_mfma_f32_16x16x32_bf16 v[84:87], v[152:155], v[214:217], v[84:87]
	s_setprio 0
	s_setprio 1
	s_cbranch_vccnz .Lp1_skip_1
	v_mfma_f32_16x16x32_bf16 v[112:115], v[174:177], v[190:193], v[112:115]
	v_mfma_f32_16x16x32_bf16 v[112:115], v[178:181], v[194:197], v[112:115]
	v_mfma_f32_16x16x32_bf16 v[104:107], v[186:189], v[194:197], v[104:107]
	v_mfma_f32_16x16x32_bf16 v[104:107], v[182:185], v[190:193], v[104:107]
	v_mfma_f32_16x16x32_bf16 v[88:91], v[182:185], v[198:201], v[88:91]
	v_mfma_f32_16x16x32_bf16 v[88:91], v[186:189], v[202:205], v[88:91]
	v_mfma_f32_16x16x32_bf16 v[96:99], v[178:181], v[202:205], v[96:99]
	v_mfma_f32_16x16x32_bf16 v[96:99], v[174:177], v[198:201], v[96:99]
	v_mfma_f32_16x16x32_bf16 v[80:83], v[174:177], v[206:209], v[80:83]
	v_mfma_f32_16x16x32_bf16 v[80:83], v[178:181], v[210:213], v[80:83]
	v_mfma_f32_16x16x32_bf16 v[72:75], v[186:189], v[210:213], v[72:75]
	v_mfma_f32_16x16x32_bf16 v[72:75], v[182:185], v[206:209], v[72:75]
	v_mfma_f32_16x16x32_bf16 v[64:67], v[182:185], v[214:217], v[64:67]
	v_mfma_f32_16x16x32_bf16 v[64:67], v[186:189], v[218:221], v[64:67]
	v_mfma_f32_16x16x32_bf16 v[68:71], v[178:181], v[218:221], v[68:71]
	v_mfma_f32_16x16x32_bf16 v[68:71], v[174:177], v[214:217], v[68:71]
; #define PG8_STAGE(bufoff, gbase, voff) do { _Pragma("unroll") for (int _i = 0; _i < 2; ++_i) \
;         __builtin_amdgcn_global_load_lds((const unsigned*)((const char*)(gbase) + (voff)[_i]), (LAS unsigned*)(lds + (bufoff) + ldsw + _i * 8192), 16, 0, 0); } while (0)
; #define PG8_LDA(dst, b, h) do { _Pragma("unroll") for (int m = 0; m < 4; ++m) _Pragma("unroll") for (int k = 0; k < 2; ++k) dst[m][k] = *(const LAS bf16x8*)(lds + PG8_SA(b, h) + aoff + m * 2048 + k * 1024); } while (0)
; #define PG8_LDB(dst, b, h) do { _Pragma("unroll") for (int n = 0; n < 2; ++n) _Pragma("unroll") for (int k = 0; k < 2; ++k) dst[n][k] = *(const LAS bf16x8*)(lds + PG8_SB(b, h) + boff + n * 2048 + k * 1024); } while (0)
; #define PG8_MMA(ai, bj, At, Bt) do { __builtin_amdgcn_s_setprio(1); _Pragma("unroll") for (int m = 0; m < 4; ++m) _Pragma("unroll") for (int n = 0; n < 2; ++n) _Pragma("unroll") for (int k = 0; k < 2; ++k) \
;         acc[ai][bj][m][n] = __builtin_amdgcn_mfma_f32_16x16x32_bf16(Bt[n][k], At[m][k], acc[ai][bj][m][n], 0, 0, 0); __builtin_amdgcn_s_setprio(0); } while (0)
; #define PG8_WAIT_V(n) asm volatile("s_waitcnt vmcnt(" #n ")" ::: "memory")
; #define PG8_WAIT_L(n) asm volatile("s_waitcnt lgkmcnt(" #n ")" ::: "memory")
; #define PG8_BAR __builtin_amdgcn_s_barrier()
; #define PG8_SCHED __builtin_amdgcn_sched_barrier(0)
; DI void gemm_phase(LAS unsigned char* lds, const Gemm g, const StaticOrder& S, const Epi& E) {
;     ...
;             PG8_LDA(At, 0, 1); PG8_STAGE(PG8_SB(0, 0), b2, voffB); PG8_STAGE(PG8_SB(0, 1), b2 + hsB, voffB); PG8_STAGE(PG8_SA(0, 0), a2, voffA);
;             PG8_WAIT_V(8); PG8_WAIT_L(0); PG8_BAR; PG8_MMA(1, 0, At, B0); PG8_MMA(1, 1, At, B1); PG8_BAR; PG8_SCHED;
;             PG8_LDB(B0, 1, 0); PG8_LDB(B1, 1, 1); PG8_SCHED; PG8_LDA(At, 1, 0); PG8_STAGE(PG8_SA(0, 1), a2 + hsA, voffA);
;             PG8_WAIT_V(8); PG8_WAIT_L(0); PG8_BAR; PG8_MMA(0, 0, At, B0); PG8_MMA(0, 1, At, B1); PG8_BAR; PG8_SCHED;
.Lp1_skip_1:
	s_setprio 0
	s_barrier
	s_add_i32 s46, s50, s12
	s_add_u32 s98, s34, 0x80
	s_addc_u32 s99, s35, 0
	s_mov_b32 m0, s46
	ds_read_b128 v[190:193], v151 offset:16384
	ds_read_b128 v[194:197], v151 offset:17408
	ds_read_b128 v[198:201], v151 offset:18432
	ds_read_b128 v[202:205], v151 offset:19456
	ds_read_b128 v[206:209], v151 offset:20480
	ds_read_b128 v[210:213], v151 offset:21504
	ds_read_b128 v[214:217], v151 offset:22528
	ds_read_b128 v[218:221], v151 offset:23552
	global_load_lds_dwordx4 v130, s[34:35]
	s_add_i32 m0, s46, 0x2000
	s_add_u32 s46, s34, 0x80000
	s_addc_u32 s47, s35, 0
	s_add_i32 s57, s51, s12
	global_load_lds_dwordx4 v134, s[34:35]
	s_mov_b32 m0, s57
	s_nop 0
	global_load_lds_dwordx4 v130, s[46:47]
	s_add_i32 m0, s57, 0x2000
	s_nop 0
	global_load_lds_dwordx4 v134, s[46:47]
	s_add_u32 s100, s38, 0x80
	s_addc_u32 s101, s39, 0
	s_mov_b32 m0, s13
	s_nop 0
	global_load_lds_dwordx4 v128, s[38:39]
	s_mov_b32 m0, s33
	s_nop 0
	global_load_lds_dwordx4 v132, s[38:39]
	s_waitcnt vmcnt(8)
	s_waitcnt lgkmcnt(0)
	s_barrier
	s_setprio 1
	s_waitcnt lgkmcnt(0)
	v_mfma_f32_16x16x32_bf16 v[60:63], v[152:155], v[190:193], v[60:63]
	v_mfma_f32_16x16x32_bf16 v[60:63], v[156:159], v[194:197], v[60:63]
	v_mfma_f32_16x16x32_bf16 v[56:59], v[170:173], v[194:197], v[56:59]
	v_mfma_f32_16x16x32_bf16 v[56:59], v[160:163], v[190:193], v[56:59]
	v_mfma_f32_16x16x32_bf16 v[44:47], v[160:163], v[198:201], v[44:47]
	v_mfma_f32_16x16x32_bf16 v[44:47], v[170:173], v[202:205], v[44:47]
	v_mfma_f32_16x16x32_bf16 v[52:55], v[156:159], v[202:205], v[52:55]
	v_mfma_f32_16x16x32_bf16 v[52:55], v[152:155], v[198:201], v[52:55]
	v_mfma_f32_16x16x32_bf16 v[36:39], v[152:155], v[206:209], v[36:39]
	v_mfma_f32_16x16x32_bf16 v[36:39], v[156:159], v[210:213], v[36:39]
	v_mfma_f32_16x16x32_bf16 v[28:31], v[170:173], v[210:213], v[28:31]
	v_mfma_f32_16x16x32_bf16 v[28:31], v[160:163], v[206:209], v[28:31]
	v_mfma_f32_16x16x32_bf16 v[12:15], v[160:163], v[214:217], v[12:15]
	v_mfma_f32_16x16x32_bf16 v[12:15], v[170:173], v[218:221], v[12:15]
	v_mfma_f32_16x16x32_bf16 v[20:23], v[156:159], v[218:221], v[20:23]
	v_mfma_f32_16x16x32_bf16 v[20:23], v[152:155], v[214:217], v[20:23]
	s_setprio 0
	s_setprio 1
	s_cbranch_vccnz .Lp1_skip_2
	v_mfma_f32_16x16x32_bf16 v[48:51], v[174:177], v[190:193], v[48:51]
	v_mfma_f32_16x16x32_bf16 v[48:51], v[178:181], v[194:197], v[48:51]
	v_mfma_f32_16x16x32_bf16 v[40:43], v[186:189], v[194:197], v[40:43]
	v_mfma_f32_16x16x32_bf16 v[40:43], v[182:185], v[190:193], v[40:43]
	v_mfma_f32_16x16x32_bf16 v[24:27], v[182:185], v[198:201], v[24:27]
	v_mfma_f32_16x16x32_bf16 v[24:27], v[186:189], v[202:205], v[24:27]
	v_mfma_f32_16x16x32_bf16 v[32:35], v[178:181], v[202:205], v[32:35]
	v_mfma_f32_16x16x32_bf16 v[32:35], v[174:177], v[198:201], v[32:35]
	v_mfma_f32_16x16x32_bf16 v[16:19], v[174:177], v[206:209], v[16:19]
	v_mfma_f32_16x16x32_bf16 v[16:19], v[178:181], v[210:213], v[16:19]
	v_mfma_f32_16x16x32_bf16 v[8:11], v[186:189], v[210:213], v[8:11]
	v_mfma_f32_16x16x32_bf16 v[8:11], v[182:185], v[206:209], v[8:11]
	v_mfma_f32_16x16x32_bf16 v[0:3], v[182:185], v[214:217], v[0:3]
	v_mfma_f32_16x16x32_bf16 v[0:3], v[186:189], v[218:221], v[0:3]
	v_mfma_f32_16x16x32_bf16 v[4:7], v[178:181], v[218:221], v[4:7]
	v_mfma_f32_16x16x32_bf16 v[4:7], v[174:177], v[214:217], v[4:7]
.Lp1_skip_2:
	s_setprio 0
	s_barrier
	s_add_i32 s46, 0, 0x18000
	v_add_u32_e32 v166, s46, v147
	s_add_i32 s47, 0, 0x1c000
	ds_read_b128 v[152:155], v166
	ds_read_b128 v[156:159], v166 offset:1024
	ds_read_b128 v[160:163], v166 offset:2048
	ds_read_b128 v[170:173], v166 offset:3072
	v_add_u32_e32 v166, s47, v147
	ds_read_b128 v[174:177], v166
	ds_read_b128 v[178:181], v166 offset:1024
	ds_read_b128 v[182:185], v166 offset:2048
	ds_read_b128 v[186:189], v166 offset:3072
	s_add_u32 s38, s38, 0x80000
	s_addc_u32 s39, s39, 0
	s_mov_b32 m0, s40
	ds_read_b128 v[190:193], v151 offset:32768
	ds_read_b128 v[194:197], v151 offset:33792
	ds_read_b128 v[198:201], v151 offset:34816
	ds_read_b128 v[202:205], v151 offset:35840
	ds_read_b128 v[206:209], v151 offset:36864
	ds_read_b128 v[210:213], v151 offset:37888
	ds_read_b128 v[214:217], v151 offset:38912
	ds_read_b128 v[218:221], v151 offset:39936
	global_load_lds_dwordx4 v128, s[38:39]
	s_mov_b32 m0, s41
	s_nop 0
	global_load_lds_dwordx4 v132, s[38:39]
	s_waitcnt vmcnt(8)
	s_waitcnt lgkmcnt(0)
	s_barrier
	s_setprio 1
	s_waitcnt lgkmcnt(0)
	v_mfma_f32_16x16x32_bf16 v[124:127], v[152:155], v[190:193], v[124:127]
	v_mfma_f32_16x16x32_bf16 v[124:127], v[156:159], v[194:197], v[124:127]
	v_mfma_f32_16x16x32_bf16 v[120:123], v[170:173], v[194:197], v[120:123]
	v_mfma_f32_16x16x32_bf16 v[120:123], v[160:163], v[190:193], v[120:123]
	v_mfma_f32_16x16x32_bf16 v[108:111], v[160:163], v[198:201], v[108:111]
	v_mfma_f32_16x16x32_bf16 v[108:111], v[170:173], v[202:205], v[108:111]
	v_mfma_f32_16x16x32_bf16 v[116:119], v[156:159], v[202:205], v[116:119]
	v_mfma_f32_16x16x32_bf16 v[116:119], v[152:155], v[198:201], v[116:119]
	v_mfma_f32_16x16x32_bf16 v[100:103], v[152:155], v[206:209], v[100:103]
	v_mfma_f32_16x16x32_bf16 v[100:103], v[156:159], v[210:213], v[100:103]
	v_mfma_f32_16x16x32_bf16 v[92:95], v[170:173], v[210:213], v[92:95]
	v_mfma_f32_16x16x32_bf16 v[92:95], v[160:163], v[206:209], v[92:95]
	v_mfma_f32_16x16x32_bf16 v[76:79], v[160:163], v[214:217], v[76:79]
	v_mfma_f32_16x16x32_bf16 v[76:79], v[170:173], v[218:221], v[76:79]
	v_mfma_f32_16x16x32_bf16 v[84:87], v[156:159], v[218:221], v[84:87]
	v_mfma_f32_16x16x32_bf16 v[84:87], v[152:155], v[214:217], v[84:87]
	s_setprio 0
	s_setprio 1
	s_cbranch_vccnz .Lp1_skip_3
	v_mfma_f32_16x16x32_bf16 v[112:115], v[174:177], v[190:193], v[112:115]
	v_mfma_f32_16x16x32_bf16 v[112:115], v[178:181], v[194:197], v[112:115]
	v_mfma_f32_16x16x32_bf16 v[104:107], v[186:189], v[194:197], v[104:107]
	v_mfma_f32_16x16x32_bf16 v[104:107], v[182:185], v[190:193], v[104:107]
	v_mfma_f32_16x16x32_bf16 v[88:91], v[182:185], v[198:201], v[88:91]
	v_mfma_f32_16x16x32_bf16 v[88:91], v[186:189], v[202:205], v[88:91]
	v_mfma_f32_16x16x32_bf16 v[96:99], v[178:181], v[202:205], v[96:99]
	v_mfma_f32_16x16x32_bf16 v[96:99], v[174:177], v[198:201], v[96:99]
	v_mfma_f32_16x16x32_bf16 v[80:83], v[174:177], v[206:209], v[80:83]
	v_mfma_f32_16x16x32_bf16 v[80:83], v[178:181], v[210:213], v[80:83]
	v_mfma_f32_16x16x32_bf16 v[72:75], v[186:189], v[210:213], v[72:75]
	v_mfma_f32_16x16x32_bf16 v[72:75], v[182:185], v[206:209], v[72:75]
	v_mfma_f32_16x16x32_bf16 v[64:67], v[182:185], v[214:217], v[64:67]
	v_mfma_f32_16x16x32_bf16 v[64:67], v[186:189], v[218:221], v[64:67]
	v_mfma_f32_16x16x32_bf16 v[68:71], v[178:181], v[218:221], v[68:71]
	v_mfma_f32_16x16x32_bf16 v[68:71], v[174:177], v[214:217], v[68:71]
; #define PG8_STAGE(bufoff, gbase, voff) do { _Pragma("unroll") for (int _i = 0; _i < 2; ++_i) \
;         __builtin_amdgcn_global_load_lds((const unsigned*)((const char*)(gbase) + (voff)[_i]), (LAS unsigned*)(lds + (bufoff) + ldsw + _i * 8192), 16, 0, 0); } while (0)
; #define PG8_LDA(dst, b, h) do { _Pragma("unroll") for (int m = 0; m < 4; ++m) _Pragma("unroll") for (int k = 0; k < 2; ++k) dst[m][k] = *(const LAS bf16x8*)(lds + PG8_SA(b, h) + aoff + m * 2048 + k * 1024); } while (0)
; #define PG8_MMA(ai, bj, At, Bt) do { __builtin_amdgcn_s_setprio(1); _Pragma("unroll") for (int m = 0; m < 4; ++m) _Pragma("unroll") for (int n = 0; n < 2; ++n) _Pragma("unroll") for (int k = 0; k < 2; ++k) \
;         acc[ai][bj][m][n] = __builtin_amdgcn_mfma_f32_16x16x32_bf16(Bt[n][k], At[m][k], acc[ai][bj][m][n], 0, 0, 0); __builtin_amdgcn_s_setprio(0); } while (0)
; #define PG8_WAIT_V(n) asm volatile("s_waitcnt vmcnt(" #n ")" ::: "memory")
; #define PG8_WAIT_L(n) asm volatile("s_waitcnt lgkmcnt(" #n ")" ::: "memory")
; #define PG8_BAR __builtin_amdgcn_s_barrier()
; #define PG8_SCHED __builtin_amdgcn_sched_barrier(0)
; DI void gemm_phase(LAS unsigned char* lds, const Gemm g, const StaticOrder& S, const Epi& E) {
;     ...
;             PG8_LDA(At, 1, 1); PG8_STAGE(PG8_SB(1, 0), b3, voffB); PG8_STAGE(PG8_SB(1, 1), b3 + hsB, voffB); PG8_STAGE(PG8_SA(1, 0), a3, voffA);
;             PG8_WAIT_V(8); PG8_WAIT_L(0); PG8_BAR; PG8_MMA(1, 0, At, B0); PG8_MMA(1, 1, At, B1); PG8_BAR; PG8_SCHED;
;         }
;         if (wr == 0) PG8_BAR;
.Lp1_skip_3:
	s_setprio 0
	s_barrier
	s_add_i32 s38, s46, s12
	s_mov_b32 m0, s38
	ds_read_b128 v[190:193], v151 offset:49152
	ds_read_b128 v[194:197], v151 offset:50176
	ds_read_b128 v[198:201], v151 offset:51200
	ds_read_b128 v[202:205], v151 offset:52224
	ds_read_b128 v[206:209], v151 offset:53248
	ds_read_b128 v[210:213], v151 offset:54272
	ds_read_b128 v[214:217], v151 offset:55296
	ds_read_b128 v[218:221], v151 offset:56320
	global_load_lds_dwordx4 v130, s[98:99]
	s_add_i32 m0, s38, 0x2000
	s_add_u32 s34, s34, 0x80080
	s_addc_u32 s35, s35, 0
	s_add_i32 s38, s47, s12
	global_load_lds_dwordx4 v134, s[98:99]
	s_mov_b32 m0, s38
	s_nop 0
	global_load_lds_dwordx4 v130, s[34:35]
	s_add_i32 m0, s38, 0x2000
	s_nop 0
	global_load_lds_dwordx4 v134, s[34:35]
	s_mov_b32 m0, s43
	s_nop 0
	global_load_lds_dwordx4 v128, s[100:101]
	s_mov_b32 m0, s48
	s_nop 0
	global_load_lds_dwordx4 v132, s[100:101]
	s_waitcnt vmcnt(8)
	s_waitcnt lgkmcnt(0)
	s_barrier
	s_setprio 1
	s_waitcnt lgkmcnt(0)
	v_mfma_f32_16x16x32_bf16 v[60:63], v[152:155], v[190:193], v[60:63]
	v_mfma_f32_16x16x32_bf16 v[60:63], v[156:159], v[194:197], v[60:63]
	v_mfma_f32_16x16x32_bf16 v[56:59], v[170:173], v[194:197], v[56:59]
	v_mfma_f32_16x16x32_bf16 v[56:59], v[160:163], v[190:193], v[56:59]
	v_mfma_f32_16x16x32_bf16 v[44:47], v[160:163], v[198:201], v[44:47]
	v_mfma_f32_16x16x32_bf16 v[44:47], v[170:173], v[202:205], v[44:47]
	v_mfma_f32_16x16x32_bf16 v[52:55], v[156:159], v[202:205], v[52:55]
	v_mfma_f32_16x16x32_bf16 v[52:55], v[152:155], v[198:201], v[52:55]
	v_mfma_f32_16x16x32_bf16 v[36:39], v[152:155], v[206:209], v[36:39]
	v_mfma_f32_16x16x32_bf16 v[36:39], v[156:159], v[210:213], v[36:39]
	v_mfma_f32_16x16x32_bf16 v[28:31], v[170:173], v[210:213], v[28:31]
	v_mfma_f32_16x16x32_bf16 v[28:31], v[160:163], v[206:209], v[28:31]
	v_mfma_f32_16x16x32_bf16 v[12:15], v[160:163], v[214:217], v[12:15]
	v_mfma_f32_16x16x32_bf16 v[12:15], v[170:173], v[218:221], v[12:15]
	v_mfma_f32_16x16x32_bf16 v[20:23], v[156:159], v[218:221], v[20:23]
	v_mfma_f32_16x16x32_bf16 v[20:23], v[152:155], v[214:217], v[20:23]
	s_setprio 0
	s_setprio 1
	s_cbranch_vccnz .Lp1_skip_4
	v_mfma_f32_16x16x32_bf16 v[48:51], v[174:177], v[190:193], v[48:51]
	v_mfma_f32_16x16x32_bf16 v[48:51], v[178:181], v[194:197], v[48:51]
	v_mfma_f32_16x16x32_bf16 v[40:43], v[186:189], v[194:197], v[40:43]
	v_mfma_f32_16x16x32_bf16 v[40:43], v[182:185], v[190:193], v[40:43]
	v_mfma_f32_16x16x32_bf16 v[24:27], v[182:185], v[198:201], v[24:27]
	v_mfma_f32_16x16x32_bf16 v[24:27], v[186:189], v[202:205], v[24:27]
	v_mfma_f32_16x16x32_bf16 v[32:35], v[178:181], v[202:205], v[32:35]
	v_mfma_f32_16x16x32_bf16 v[32:35], v[174:177], v[198:201], v[32:35]
	v_mfma_f32_16x16x32_bf16 v[16:19], v[174:177], v[206:209], v[16:19]
	v_mfma_f32_16x16x32_bf16 v[16:19], v[178:181], v[210:213], v[16:19]
	v_mfma_f32_16x16x32_bf16 v[8:11], v[186:189], v[210:213], v[8:11]
	v_mfma_f32_16x16x32_bf16 v[8:11], v[182:185], v[206:209], v[8:11]
	v_mfma_f32_16x16x32_bf16 v[0:3], v[182:185], v[214:217], v[0:3]
	v_mfma_f32_16x16x32_bf16 v[0:3], v[186:189], v[218:221], v[0:3]
	v_mfma_f32_16x16x32_bf16 v[4:7], v[178:181], v[218:221], v[4:7]
	v_mfma_f32_16x16x32_bf16 v[4:7], v[174:177], v[214:217], v[4:7]
.Lp1_skip_4:
	s_setprio 0
	s_barrier
	s_add_i32 s56, s56, 2
	s_add_u32 s30, s30, 0x100
	s_addc_u32 s31, s31, 0
	s_add_u32 s54, s54, 0x100
	s_addc_u32 s55, s55, 0
	s_cmp_gt_u32 s56, 29
	s_cbranch_scc0 .LBB0_177
	s_and_b64 vcc, exec, s[18:19]
	s_cbranch_vccz .LBB0_180
	s_barrier
